# attention PV gaps: row-sum adds and bf16 packs software-pipelined one gap behind their exps; remaining VGPR-address DMA sites to scalar-base form
# baseline (speedup 1.0000x reference)
.LBB0_188:
	s_waitcnt lgkmcnt(3)
	v_mfma_f32_32x32x16_bf16 v[34:49], v[126:129], v[162:165], v[34:49]
	ds_read_b128 v[126:129], v212 offset:49152
	s_nop 0
	v_exp_f32_e32 v132, v82
	v_exp_f32_e32 v133, v83
	s_waitcnt lgkmcnt(3)
	v_mfma_f32_32x32x16_bf16 v[50:65], v[122:125], v[162:165], v[50:65]
	ds_read_b128 v[122:125], v212 offset:53248
	v_exp_f32_e32 v134, v84
	v_exp_f32_e32 v135, v85
	v_add_f32_e32 v136, v1, v132
	v_add_f32_e32 v137, v1, v133
	v_cvt_pk_bf16_f32 v166, v132, v133
	s_add_i32 s22, s23, 2
	s_cmp_lt_u32 s22, s17
	s_cselect_b64 s[26:27], -1, 0
	s_cmp_ge_u32 s22, s17
	s_cbranch_scc1 .LBB0_190
	s_lshl_b32 s40, s48, 14
	s_add_i32 m0, s11, s40
	s_add_u32 s100, s8, s80
	s_addc_u32 s101, s9, s81
	global_load_lds_dwordx4 v214, s[100:101]
.LBB0_190:
	s_waitcnt lgkmcnt(3)
	v_mfma_f32_32x32x16_bf16 v[18:33], v[118:121], v[162:165], v[18:33]
	ds_read_b128 v[118:121], v212 offset:57344
	v_exp_f32_e32 v132, v86
	v_exp_f32_e32 v133, v87
	v_add_f32_e32 v136, v136, v134
	v_add_f32_e32 v137, v137, v135
	v_cvt_pk_bf16_f32 v167, v134, v135
	s_waitcnt lgkmcnt(3)
	v_mfma_f32_32x32x16_bf16 v[2:17], v[114:117], v[162:165], v[2:17]
	ds_read_b128 v[114:117], v212 offset:61440
	v_exp_f32_e32 v134, v88
	v_exp_f32_e32 v135, v89
	v_add_f32_e32 v136, v136, v132
	v_add_f32_e32 v137, v137, v133
	v_cvt_pk_bf16_f32 v168, v132, v133
	s_waitcnt lgkmcnt(3)
	v_mfma_f32_32x32x16_bf16 v[34:49], v[126:129], v[170:173], v[34:49]
	v_add_u32_e32 v130, s54, v246
	ds_read_b128 v[126:129], v130 offset:49152
	v_exp_f32_e32 v132, v90
	v_exp_f32_e32 v133, v91
	v_add_f32_e32 v136, v136, v134
	v_add_f32_e32 v137, v137, v135
	v_cvt_pk_bf16_f32 v169, v134, v135
	s_waitcnt lgkmcnt(3)
	v_mfma_f32_32x32x16_bf16 v[50:65], v[122:125], v[170:173], v[50:65]
	ds_read_b128 v[122:125], v130 offset:53248
	v_exp_f32_e32 v134, v92
	v_exp_f32_e32 v135, v93
	v_add_f32_e32 v136, v136, v132
	v_add_f32_e32 v137, v137, v133
	v_cvt_pk_bf16_f32 v174, v132, v133
	s_andn2_b64 vcc, exec, s[26:27]
	s_cbranch_vccnz .LBB0_192
	s_lshl_b32 s26, s48, 14
	s_add_i32 s26, s11, s26
	s_add_i32 m0, s26, 0x2000
	s_add_u32 s100, s8, s62
	s_addc_u32 s101, s9, s63
	global_load_lds_dwordx4 v214, s[100:101]
.LBB0_192:
	s_waitcnt lgkmcnt(3)
	v_mfma_f32_32x32x16_bf16 v[18:33], v[118:121], v[170:173], v[18:33]
	ds_read_b128 v[118:121], v130 offset:57344
	v_exp_f32_e32 v132, v94
	v_exp_f32_e32 v133, v95
	v_add_f32_e32 v136, v136, v134
	v_add_f32_e32 v137, v137, v135
	v_cvt_pk_bf16_f32 v175, v134, v135
	s_waitcnt lgkmcnt(3)
	v_mfma_f32_32x32x16_bf16 v[2:17], v[114:117], v[170:173], v[2:17]
	ds_read_b128 v[114:117], v130 offset:61440
	v_exp_f32_e32 v134, v96
	v_exp_f32_e32 v135, v97
	v_add_f32_e32 v136, v136, v132
	v_add_f32_e32 v137, v137, v133
	v_cvt_pk_bf16_f32 v176, v132, v133
	s_waitcnt lgkmcnt(3)
	v_mfma_f32_32x32x16_bf16 v[34:49], v[126:129], v[178:181], v[34:49]
	v_add_u32_e32 v130, s54, v247
	ds_read_b128 v[126:129], v130 offset:49152
	v_exp_f32_e32 v132, v98
	v_exp_f32_e32 v133, v99
	v_add_f32_e32 v136, v136, v134
	v_add_f32_e32 v137, v137, v135
	v_cvt_pk_bf16_f32 v177, v134, v135
	s_waitcnt lgkmcnt(3)
	v_mfma_f32_32x32x16_bf16 v[50:65], v[122:125], v[178:181], v[50:65]
	v_exp_f32_e32 v134, v100
	v_exp_f32_e32 v135, v101
	v_add_f32_e32 v136, v136, v132
	v_add_f32_e32 v137, v137, v133
	v_cvt_pk_bf16_f32 v182, v132, v133
	ds_read_b128 v[122:125], v130 offset:53248
	v_cndmask_b32_e64 v138, 0, 1, s[88:89]
	v_cmp_ne_u32_e64 s[40:41], 1, v138
	s_andn2_b64 vcc, exec, s[88:89]
	s_cbranch_vccnz .LBB0_194
	s_lshl_b32 s26, s31, 14
	s_add_i32 s26, s11, s26
	s_add_i32 m0, s26, 0xc000
	s_add_u32 s100, s8, s96
	s_addc_u32 s101, s9, s97
	global_load_lds_dwordx4 v216, s[100:101]
.LBB0_194:
	s_waitcnt lgkmcnt(3)
	v_mfma_f32_32x32x16_bf16 v[18:33], v[118:121], v[178:181], v[18:33]
	ds_read_b128 v[118:121], v130 offset:57344
	v_exp_f32_e32 v132, v102
	v_exp_f32_e32 v133, v103
	v_add_f32_e32 v136, v136, v134
	v_add_f32_e32 v137, v137, v135
	v_cvt_pk_bf16_f32 v183, v134, v135
	s_waitcnt lgkmcnt(3)
	v_mfma_f32_32x32x16_bf16 v[2:17], v[114:117], v[178:181], v[2:17]
	ds_read_b128 v[114:117], v130 offset:61440
	v_exp_f32_e32 v134, v104
	v_exp_f32_e32 v135, v105
	v_add_f32_e32 v136, v136, v132
	v_add_f32_e32 v137, v137, v133
	v_cvt_pk_bf16_f32 v184, v132, v133
	s_waitcnt lgkmcnt(3)
	v_mfma_f32_32x32x16_bf16 v[34:49], v[126:129], v[186:189], v[34:49]
	v_exp_f32_e32 v132, v106
	v_exp_f32_e32 v133, v107
	v_add_f32_e32 v136, v136, v134
	v_add_f32_e32 v137, v137, v135
	v_cvt_pk_bf16_f32 v185, v134, v135
	s_waitcnt lgkmcnt(2)
	v_mfma_f32_32x32x16_bf16 v[50:65], v[122:125], v[186:189], v[50:65]
	v_exp_f32_e32 v134, v108
	v_exp_f32_e32 v135, v109
	v_add_f32_e32 v136, v136, v132
	v_add_f32_e32 v137, v137, v133
	v_cvt_pk_bf16_f32 v190, v132, v133
	s_and_b64 vcc, exec, s[40:41]
	s_cbranch_vccnz .LBB0_196
	s_lshl_b32 s26, s31, 14
	s_add_i32 s26, s11, s26
	s_add_i32 m0, s26, 0xe000
	s_add_u32 s100, s8, s58
	s_addc_u32 s101, s9, s59
	global_load_lds_dwordx4 v216, s[100:101]
.LBB0_196:
	s_waitcnt lgkmcnt(1)
	v_mfma_f32_32x32x16_bf16 v[18:33], v[118:121], v[186:189], v[18:33]
	v_exp_f32_e32 v132, v110
	v_exp_f32_e32 v133, v111
	v_add_f32_e32 v136, v136, v134
	v_add_f32_e32 v137, v137, v135
	v_cvt_pk_bf16_f32 v191, v134, v135
	s_waitcnt lgkmcnt(0)
	v_mfma_f32_32x32x16_bf16 v[2:17], v[114:117], v[186:189], v[2:17]
	v_exp_f32_e32 v134, v112
	v_exp_f32_e32 v135, v113
	v_add_f32_e32 v136, v136, v132
	v_add_f32_e32 v137, v137, v133
	v_cvt_pk_bf16_f32 v192, v132, v133
	v_add_f32_e32 v136, v136, v134
	v_add_f32_e32 v137, v137, v135
	v_cvt_pk_bf16_f32 v193, v134, v135
	v_add_f32_e32 v212, v136, v137
	v_cmp_nge_f32_e32 vcc, s7, v212
	s_cbranch_vccz .LBB0_198
	v_max_f32_e32 v66, v99, v99
	v_max_f32_e32 v67, v83, v83
	v_max_f32_e32 v66, v67, v66
	v_max3_f32 v66, v82, v98, v66
	v_max3_f32 v67, v100, v85, v101
	v_max3_f32 v66, v66, v84, v67
	v_max3_f32 v67, v102, v87, v103
	v_max3_f32 v66, v66, v86, v67
	v_max3_f32 v67, v104, v89, v105
	v_max3_f32 v66, v66, v88, v67
	v_max3_f32 v67, v106, v91, v107
	v_max3_f32 v66, v66, v90, v67
	v_max3_f32 v67, v108, v93, v109
	v_max3_f32 v66, v66, v92, v67
	v_max3_f32 v67, v110, v95, v111
	v_max3_f32 v66, v66, v94, v67
	v_max3_f32 v67, v112, v97, v113
	v_max3_f32 v66, v66, v96, v67
	v_mov_b32_e32 v67, v66
	s_nop 1
	v_permlane32_swap_b32_e32 v66, v67
	v_max_f32_e32 v67, v67, v67
	v_max_f32_e32 v66, v66, v66
	v_max_f32_e32 v66, v66, v67
	v_cmp_lt_f32_e32 vcc, s57, v66
	s_nop 1
	v_cndmask_b32_e32 v68, 0, v66, vcc
	v_sub_f32_e32 v66, v82, v68
	v_exp_f32_e32 v116, v66
	v_sub_f32_e32 v66, v98, v68
	v_exp_f32_e32 v117, v66
	v_sub_f32_e32 v66, v83, v68
	v_exp_f32_e32 v118, v66
	v_sub_f32_e32 v66, v99, v68
	v_exp_f32_e32 v119, v66
	v_sub_f32_e32 v66, v84, v68
	v_exp_f32_e32 v98, v66
	v_sub_f32_e32 v66, v100, v68
	v_exp_f32_e32 v82, v66
	v_add_f32_e32 v66, v117, v116
	v_add_f32_e32 v99, 0, v66
	v_add_f32_e32 v83, v119, v118
	v_pk_add_f32 v[66:67], v[82:83], v[98:99]
	v_cvt_pk_bf16_f32 v166, v116, v118
	v_pk_add_f32 v[114:115], v[66:67], v[66:67] op_sel_hi:[0,1]
	v_sub_f32_e32 v66, v85, v68
	v_exp_f32_e32 v83, v66
	v_sub_f32_e32 v66, v101, v68
	v_exp_f32_e32 v99, v66
	v_sub_f32_e32 v66, v86, v68
	v_exp_f32_e32 v114, v66
	v_sub_f32_e32 v66, v102, v68
	v_exp_f32_e32 v84, v66
	v_add_f32_e32 v85, v99, v83
	v_cvt_pk_bf16_f32 v167, v98, v83
	v_cvt_pk_bf16_f32 v182, v117, v119
	v_pk_add_f32 v[66:67], v[84:85], v[114:115]
	v_cvt_pk_bf16_f32 v183, v82, v99
	v_pk_add_f32 v[100:101], v[66:67], v[66:67] op_sel_hi:[0,1]
	v_sub_f32_e32 v66, v87, v68
	v_exp_f32_e32 v85, v66
	v_sub_f32_e32 v66, v103, v68
	v_exp_f32_e32 v115, v66
	v_sub_f32_e32 v66, v88, v68
	v_exp_f32_e32 v100, v66
	v_sub_f32_e32 v66, v104, v68
	v_exp_f32_e32 v86, v66
	v_add_f32_e32 v87, v115, v85
	v_cvt_pk_bf16_f32 v168, v114, v85
	v_cvt_pk_bf16_f32 v184, v84, v115
	v_pk_add_f32 v[66:67], v[86:87], v[100:101]
	s_nop 0
	v_pk_add_f32 v[102:103], v[66:67], v[66:67] op_sel_hi:[0,1]
	v_sub_f32_e32 v66, v89, v68
	v_exp_f32_e32 v87, v66
	v_sub_f32_e32 v66, v105, v68
	v_exp_f32_e32 v101, v66
	v_sub_f32_e32 v66, v90, v68
	v_exp_f32_e32 v102, v66
	v_sub_f32_e32 v66, v106, v68
	v_exp_f32_e32 v88, v66
	v_add_f32_e32 v89, v101, v87
	v_cvt_pk_bf16_f32 v169, v100, v87
	v_cvt_pk_bf16_f32 v185, v86, v101
	v_pk_add_f32 v[66:67], v[88:89], v[102:103]
	s_nop 0
	v_pk_add_f32 v[104:105], v[66:67], v[66:67] op_sel_hi:[0,1]
	v_sub_f32_e32 v66, v91, v68
	v_exp_f32_e32 v89, v66
	v_sub_f32_e32 v66, v107, v68
	v_exp_f32_e32 v103, v66
	v_sub_f32_e32 v66, v92, v68
	v_exp_f32_e32 v104, v66
	v_sub_f32_e32 v66, v108, v68
	v_exp_f32_e32 v90, v66
	v_sub_f32_e32 v66, v97, v68
	v_add_f32_e32 v91, v103, v89
	v_exp_f32_e32 v97, v66
	v_pk_add_f32 v[66:67], v[90:91], v[104:105]
	v_cvt_pk_bf16_f32 v174, v102, v89
	v_pk_add_f32 v[106:107], v[66:67], v[66:67] op_sel_hi:[0,1]
	v_sub_f32_e32 v66, v93, v68
	v_exp_f32_e32 v91, v66
	v_sub_f32_e32 v66, v109, v68
	v_exp_f32_e32 v105, v66
	v_sub_f32_e32 v66, v94, v68
	v_exp_f32_e32 v106, v66
	v_sub_f32_e32 v66, v110, v68
	v_exp_f32_e32 v92, v66
	v_sub_f32_e32 v66, v113, v68
	v_add_f32_e32 v93, v105, v91
	v_exp_f32_e32 v110, v66
	v_pk_add_f32 v[66:67], v[92:93], v[106:107]
	v_cvt_pk_bf16_f32 v175, v104, v91
	v_pk_add_f32 v[108:109], v[66:67], v[66:67] op_sel_hi:[0,1]
	v_sub_f32_e32 v66, v95, v68
	v_exp_f32_e32 v93, v66
	v_sub_f32_e32 v66, v111, v68
	v_exp_f32_e32 v107, v66
	v_sub_f32_e32 v66, v96, v68
	v_exp_f32_e32 v108, v66
	v_sub_f32_e32 v66, v112, v68
	v_exp_f32_e32 v94, v66
	v_add_f32_e32 v95, v107, v93
	v_exp_f32_e64 v96, -v68
	v_add_f32_e32 v212, v110, v97
	v_pk_add_f32 v[66:67], v[94:95], v[108:109]
	v_cvt_pk_bf16_f32 v176, v106, v93
	v_pk_add_f32 v[66:67], v[66:67], v[66:67] op_sel:[0,1] op_sel_hi:[1,0]
	v_pk_mul_f32 v[48:49], v[48:49], v[96:97] op_sel_hi:[1,0]
	v_mov_b32_e32 v67, v68
	v_pk_add_f32 v[212:213], v[212:213], v[66:67]
	v_pk_mul_f32 v[46:47], v[46:47], v[96:97] op_sel_hi:[1,0]
	v_xor_b32_e32 v66, 0x80000000, v213
	v_mov_b32_e32 v67, v66
	v_mov_b32_e32 v68, v66
	v_mov_b32_e32 v69, v66
	v_mov_b32_e32 v70, v66
	v_mov_b32_e32 v71, v66
	v_mov_b32_e32 v72, v66
	v_mov_b32_e32 v73, v66
	v_mov_b32_e32 v74, v66
	v_mov_b32_e32 v75, v66
	v_mov_b32_e32 v76, v66
	v_mov_b32_e32 v77, v66
	v_mov_b32_e32 v78, v66
	v_mov_b32_e32 v79, v66
	v_mov_b32_e32 v80, v66
	v_mov_b32_e32 v81, v66
	v_pk_mul_f32 v[44:45], v[44:45], v[96:97] op_sel_hi:[1,0]
	v_pk_mul_f32 v[42:43], v[42:43], v[96:97] op_sel_hi:[1,0]
	v_pk_mul_f32 v[40:41], v[40:41], v[96:97] op_sel_hi:[1,0]
	v_pk_mul_f32 v[38:39], v[38:39], v[96:97] op_sel_hi:[1,0]
	v_pk_mul_f32 v[36:37], v[36:37], v[96:97] op_sel_hi:[1,0]
	v_pk_mul_f32 v[34:35], v[34:35], v[96:97] op_sel_hi:[1,0]
	v_pk_mul_f32 v[64:65], v[64:65], v[96:97] op_sel_hi:[1,0]
	v_pk_mul_f32 v[62:63], v[62:63], v[96:97] op_sel_hi:[1,0]
	v_pk_mul_f32 v[60:61], v[60:61], v[96:97] op_sel_hi:[1,0]
	v_pk_mul_f32 v[58:59], v[58:59], v[96:97] op_sel_hi:[1,0]
	v_pk_mul_f32 v[56:57], v[56:57], v[96:97] op_sel_hi:[1,0]
	v_pk_mul_f32 v[54:55], v[54:55], v[96:97] op_sel_hi:[1,0]
	v_pk_mul_f32 v[52:53], v[52:53], v[96:97] op_sel_hi:[1,0]
	v_pk_mul_f32 v[50:51], v[50:51], v[96:97] op_sel_hi:[1,0]
	v_pk_mul_f32 v[32:33], v[32:33], v[96:97] op_sel_hi:[1,0]
	v_pk_mul_f32 v[30:31], v[30:31], v[96:97] op_sel_hi:[1,0]
	v_pk_mul_f32 v[28:29], v[28:29], v[96:97] op_sel_hi:[1,0]
	v_pk_mul_f32 v[26:27], v[26:27], v[96:97] op_sel_hi:[1,0]
	v_pk_mul_f32 v[24:25], v[24:25], v[96:97] op_sel_hi:[1,0]
	v_pk_mul_f32 v[22:23], v[22:23], v[96:97] op_sel_hi:[1,0]
	v_pk_mul_f32 v[20:21], v[20:21], v[96:97] op_sel_hi:[1,0]
	v_pk_mul_f32 v[18:19], v[18:19], v[96:97] op_sel_hi:[1,0]
	v_pk_mul_f32 v[16:17], v[16:17], v[96:97] op_sel_hi:[1,0]
	v_pk_mul_f32 v[14:15], v[14:15], v[96:97] op_sel_hi:[1,0]
	v_pk_mul_f32 v[12:13], v[12:13], v[96:97] op_sel_hi:[1,0]
	v_pk_mul_f32 v[10:11], v[10:11], v[96:97] op_sel_hi:[1,0]
	v_pk_mul_f32 v[8:9], v[8:9], v[96:97] op_sel_hi:[1,0]
	v_pk_mul_f32 v[6:7], v[6:7], v[96:97] op_sel_hi:[1,0]
	v_pk_mul_f32 v[4:5], v[4:5], v[96:97] op_sel_hi:[1,0]
	v_pk_mul_f32 v[2:3], v[2:3], v[96:97] op_sel_hi:[1,0]
	v_mul_f32_e32 v242, v242, v96
	v_cvt_pk_bf16_f32 v177, v108, v97
	v_cvt_pk_bf16_f32 v190, v88, v103
	v_cvt_pk_bf16_f32 v191, v90, v105
	v_cvt_pk_bf16_f32 v192, v92, v107
	v_cvt_pk_bf16_f32 v193, v94, v110

.LBB0_228:
	s_waitcnt lgkmcnt(3)
	v_mfma_f32_32x32x16_bf16 v[34:49], v[126:129], v[166:169], v[34:49]
	ds_read_b128 v[126:129], v212 offset:49152
	s_nop 0
	v_exp_f32_e32 v132, v82
	v_exp_f32_e32 v133, v83
	s_waitcnt lgkmcnt(3)
	v_mfma_f32_32x32x16_bf16 v[50:65], v[122:125], v[166:169], v[50:65]
	ds_read_b128 v[122:125], v212 offset:53248
	v_exp_f32_e32 v134, v84
	v_exp_f32_e32 v135, v85
	v_add_f32_e32 v136, v1, v132
	v_add_f32_e32 v137, v1, v133
	v_cvt_pk_bf16_f32 v162, v132, v133
	s_add_i32 s23, s23, 3
	s_cmp_le_u32 s23, s16
	s_cselect_b64 s[26:27], -1, 0
	s_cmp_gt_u32 s23, s16
	s_cbranch_scc1 .LBB0_230
	s_lshl_b32 s23, s48, 14
	s_add_u32 s100, s8, s50
	s_addc_u32 s101, s9, s51
	s_add_i32 m0, s11, s23
	s_nop 0
	global_load_lds_dwordx4 v214, s[100:101]
.LBB0_230:
	s_waitcnt lgkmcnt(3)
	v_mfma_f32_32x32x16_bf16 v[18:33], v[118:121], v[166:169], v[18:33]
	ds_read_b128 v[118:121], v212 offset:57344
	v_exp_f32_e32 v132, v86
	v_exp_f32_e32 v133, v87
	v_add_f32_e32 v136, v136, v134
	v_add_f32_e32 v137, v137, v135
	v_cvt_pk_bf16_f32 v163, v134, v135
	s_waitcnt lgkmcnt(3)
	v_mfma_f32_32x32x16_bf16 v[2:17], v[114:117], v[166:169], v[2:17]
	ds_read_b128 v[114:117], v212 offset:61440
	v_exp_f32_e32 v134, v88
	v_exp_f32_e32 v135, v89
	v_add_f32_e32 v136, v136, v132
	v_add_f32_e32 v137, v137, v133
	v_cvt_pk_bf16_f32 v164, v132, v133
	s_waitcnt lgkmcnt(3)
	v_mfma_f32_32x32x16_bf16 v[34:49], v[126:129], v[174:177], v[34:49]
	v_add_u32_e32 v130, s54, v246
	ds_read_b128 v[126:129], v130 offset:49152
	v_exp_f32_e32 v132, v90
	v_exp_f32_e32 v133, v91
	v_add_f32_e32 v136, v136, v134
	v_add_f32_e32 v137, v137, v135
	v_cvt_pk_bf16_f32 v165, v134, v135
	s_waitcnt lgkmcnt(3)
	v_mfma_f32_32x32x16_bf16 v[50:65], v[122:125], v[174:177], v[50:65]
	ds_read_b128 v[122:125], v130 offset:53248
	v_exp_f32_e32 v134, v92
	v_exp_f32_e32 v135, v93
	v_add_f32_e32 v136, v136, v132
	v_add_f32_e32 v137, v137, v133
	v_cvt_pk_bf16_f32 v170, v132, v133
	s_andn2_b64 vcc, exec, s[26:27]
	s_cbranch_vccnz .LBB0_232
	s_lshl_b32 s23, s48, 14
	s_add_i32 s23, s11, s23
	s_add_u32 s100, s8, s4
	s_addc_u32 s101, s9, s5
	s_add_i32 m0, s23, 0x2000
	s_nop 0
	global_load_lds_dwordx4 v214, s[100:101]
.LBB0_232:
	s_waitcnt lgkmcnt(3)
	v_mfma_f32_32x32x16_bf16 v[18:33], v[118:121], v[174:177], v[18:33]
	ds_read_b128 v[118:121], v130 offset:57344
	v_exp_f32_e32 v132, v94
	v_exp_f32_e32 v133, v95
	v_add_f32_e32 v136, v136, v134
	v_add_f32_e32 v137, v137, v135
	v_cvt_pk_bf16_f32 v171, v134, v135
	s_waitcnt lgkmcnt(3)
	v_mfma_f32_32x32x16_bf16 v[2:17], v[114:117], v[174:177], v[2:17]
	ds_read_b128 v[114:117], v130 offset:61440
	v_exp_f32_e32 v134, v96
	v_exp_f32_e32 v135, v97
	v_add_f32_e32 v136, v136, v132
	v_add_f32_e32 v137, v137, v133
	v_cvt_pk_bf16_f32 v172, v132, v133
	s_waitcnt lgkmcnt(3)
	v_mfma_f32_32x32x16_bf16 v[34:49], v[126:129], v[182:185], v[34:49]
	v_add_u32_e32 v130, s54, v247
	ds_read_b128 v[126:129], v130 offset:49152
	v_exp_f32_e32 v132, v98
	v_exp_f32_e32 v133, v99
	v_add_f32_e32 v136, v136, v134
	v_add_f32_e32 v137, v137, v135
	v_cvt_pk_bf16_f32 v173, v134, v135
	s_waitcnt lgkmcnt(3)
	v_mfma_f32_32x32x16_bf16 v[50:65], v[122:125], v[182:185], v[50:65]
	v_exp_f32_e32 v134, v100
	v_exp_f32_e32 v135, v101
	v_add_f32_e32 v136, v136, v132
	v_add_f32_e32 v137, v137, v133
	v_cvt_pk_bf16_f32 v178, v132, v133
	ds_read_b128 v[122:125], v130 offset:53248
	v_cndmask_b32_e64 v138, 0, 1, s[88:89]
	v_cmp_ne_u32_e64 s[40:41], 1, v138
	s_andn2_b64 vcc, exec, s[88:89]
	s_cbranch_vccnz .LBB0_234
	s_lshl_b32 s23, s31, 14
	s_add_i32 s23, s11, s23
	s_add_i32 m0, s23, 0xc000
	s_add_u32 s100, s8, s0
	s_addc_u32 s101, s9, s1
	global_load_lds_dwordx4 v216, s[100:101]
.LBB0_234:
	s_waitcnt lgkmcnt(3)
	v_mfma_f32_32x32x16_bf16 v[18:33], v[118:121], v[182:185], v[18:33]
	ds_read_b128 v[118:121], v130 offset:57344
	v_exp_f32_e32 v132, v102
	v_exp_f32_e32 v133, v103
	v_add_f32_e32 v136, v136, v134
	v_add_f32_e32 v137, v137, v135
	v_cvt_pk_bf16_f32 v179, v134, v135
	s_waitcnt lgkmcnt(3)
	v_mfma_f32_32x32x16_bf16 v[2:17], v[114:117], v[182:185], v[2:17]
	ds_read_b128 v[114:117], v130 offset:61440
	v_exp_f32_e32 v134, v104
	v_exp_f32_e32 v135, v105
	v_add_f32_e32 v136, v136, v132
	v_add_f32_e32 v137, v137, v133
	v_cvt_pk_bf16_f32 v180, v132, v133
	s_waitcnt lgkmcnt(3)
	v_mfma_f32_32x32x16_bf16 v[34:49], v[126:129], v[190:193], v[34:49]
	v_exp_f32_e32 v132, v106
	v_exp_f32_e32 v133, v107
	v_add_f32_e32 v136, v136, v134
	v_add_f32_e32 v137, v137, v135
	v_cvt_pk_bf16_f32 v181, v134, v135
	s_waitcnt lgkmcnt(2)
	v_mfma_f32_32x32x16_bf16 v[50:65], v[122:125], v[190:193], v[50:65]
	v_exp_f32_e32 v134, v108
	v_exp_f32_e32 v135, v109
	v_add_f32_e32 v136, v136, v132
	v_add_f32_e32 v137, v137, v133
	v_cvt_pk_bf16_f32 v186, v132, v133
	s_and_b64 vcc, exec, s[40:41]
	s_cbranch_vccnz .LBB0_236
	s_lshl_b32 s23, s31, 14
	s_add_i32 s23, s11, s23
	s_add_u32 s100, s8, s52
	s_addc_u32 s101, s9, s53
	s_add_i32 m0, s23, 0xe000
	s_nop 0
	global_load_lds_dwordx4 v216, s[100:101]
.LBB0_236:
	s_waitcnt lgkmcnt(1)
	v_mfma_f32_32x32x16_bf16 v[18:33], v[118:121], v[190:193], v[18:33]
	v_exp_f32_e32 v132, v110
	v_exp_f32_e32 v133, v111
	v_add_f32_e32 v136, v136, v134
	v_add_f32_e32 v137, v137, v135
	v_cvt_pk_bf16_f32 v187, v134, v135
	s_waitcnt lgkmcnt(0)
	v_mfma_f32_32x32x16_bf16 v[2:17], v[114:117], v[190:193], v[2:17]
	v_exp_f32_e32 v134, v112
	v_exp_f32_e32 v135, v113
	v_add_f32_e32 v136, v136, v132
	v_add_f32_e32 v137, v137, v133
	v_cvt_pk_bf16_f32 v188, v132, v133
	v_add_f32_e32 v136, v136, v134
	v_add_f32_e32 v137, v137, v135
	v_cvt_pk_bf16_f32 v189, v134, v135
	v_add_f32_e32 v212, v136, v137
	v_cmp_nge_f32_e32 vcc, s7, v212
	s_cbranch_vccz .LBB0_238
	v_max_f32_e32 v66, v99, v99
	v_max_f32_e32 v67, v83, v83
	v_max_f32_e32 v66, v67, v66
	v_max3_f32 v66, v82, v98, v66
	v_max3_f32 v67, v100, v85, v101
	v_max3_f32 v66, v66, v84, v67
	v_max3_f32 v67, v102, v87, v103
	v_max3_f32 v66, v66, v86, v67
	v_max3_f32 v67, v104, v89, v105
	v_max3_f32 v66, v66, v88, v67
	v_max3_f32 v67, v106, v91, v107
	v_max3_f32 v66, v66, v90, v67
	v_max3_f32 v67, v108, v93, v109
	v_max3_f32 v66, v66, v92, v67
	v_max3_f32 v67, v110, v95, v111
	v_max3_f32 v66, v66, v94, v67
	v_max3_f32 v67, v112, v97, v113
	v_max3_f32 v66, v66, v96, v67
	v_mov_b32_e32 v67, v66
	s_nop 1
	v_permlane32_swap_b32_e32 v66, v67
	v_max_f32_e32 v67, v67, v67
	v_max_f32_e32 v66, v66, v66
	v_max_f32_e32 v66, v66, v67
	v_cmp_lt_f32_e32 vcc, s57, v66
	s_nop 1
	v_cndmask_b32_e32 v68, 0, v66, vcc
	v_sub_f32_e32 v66, v82, v68
	v_exp_f32_e32 v116, v66
	v_sub_f32_e32 v66, v98, v68
	v_exp_f32_e32 v117, v66
	v_sub_f32_e32 v66, v83, v68
	v_exp_f32_e32 v118, v66
	v_sub_f32_e32 v66, v99, v68
	v_exp_f32_e32 v119, v66
	v_sub_f32_e32 v66, v84, v68
	v_exp_f32_e32 v114, v66
	v_sub_f32_e32 v66, v100, v68
	v_exp_f32_e32 v82, v66
	v_add_f32_e32 v66, v116, v117
	v_add_f32_e32 v83, 0, v66
	v_add_f32_e32 v115, v118, v119
	v_pk_add_f32 v[66:67], v[114:115], v[82:83]
	v_cvt_pk_bf16_f32 v162, v116, v118
	v_pk_add_f32 v[98:99], v[66:67], v[66:67] op_sel_hi:[0,1]
	v_sub_f32_e32 v66, v85, v68
	v_exp_f32_e32 v83, v66
	v_sub_f32_e32 v66, v101, v68
	v_exp_f32_e32 v115, v66
	v_sub_f32_e32 v66, v86, v68
	v_exp_f32_e32 v100, v66
	v_sub_f32_e32 v66, v102, v68
	v_exp_f32_e32 v98, v66
	v_add_f32_e32 v101, v83, v115
	v_cvt_pk_bf16_f32 v163, v114, v83
	v_cvt_pk_bf16_f32 v178, v117, v119
	v_pk_add_f32 v[66:67], v[100:101], v[98:99]
	v_cvt_pk_bf16_f32 v179, v82, v115
	v_pk_add_f32 v[84:85], v[66:67], v[66:67] op_sel_hi:[0,1]
	v_sub_f32_e32 v66, v87, v68
	v_exp_f32_e32 v99, v66
	v_sub_f32_e32 v66, v103, v68
	v_exp_f32_e32 v101, v66
	v_sub_f32_e32 v66, v88, v68
	v_exp_f32_e32 v102, v66
	v_sub_f32_e32 v66, v104, v68
	v_exp_f32_e32 v84, v66
	v_add_f32_e32 v103, v99, v101
	v_cvt_pk_bf16_f32 v164, v100, v99
	v_cvt_pk_bf16_f32 v180, v98, v101
	v_pk_add_f32 v[66:67], v[102:103], v[84:85]
	s_nop 0
	v_pk_add_f32 v[86:87], v[66:67], v[66:67] op_sel_hi:[0,1]
	v_sub_f32_e32 v66, v89, v68
	v_exp_f32_e32 v85, v66
	v_sub_f32_e32 v66, v105, v68
	v_exp_f32_e32 v103, v66
	v_sub_f32_e32 v66, v90, v68
	v_exp_f32_e32 v104, v66
	v_sub_f32_e32 v66, v106, v68
	v_exp_f32_e32 v86, v66
	v_add_f32_e32 v105, v85, v103
	v_cvt_pk_bf16_f32 v165, v102, v85
	v_cvt_pk_bf16_f32 v181, v84, v103
	v_pk_add_f32 v[66:67], v[104:105], v[86:87]
	s_nop 0
	v_pk_add_f32 v[88:89], v[66:67], v[66:67] op_sel_hi:[0,1]
	v_sub_f32_e32 v66, v91, v68
	v_exp_f32_e32 v87, v66
	v_sub_f32_e32 v66, v107, v68
	v_exp_f32_e32 v105, v66
	v_sub_f32_e32 v66, v92, v68
	v_exp_f32_e32 v90, v66
	v_sub_f32_e32 v66, v108, v68
	v_exp_f32_e32 v88, v66
	v_sub_f32_e32 v66, v97, v68
	v_add_f32_e32 v91, v87, v105
	v_exp_f32_e32 v97, v66
	v_pk_add_f32 v[66:67], v[90:91], v[88:89]
	v_cvt_pk_bf16_f32 v170, v104, v87
	v_pk_add_f32 v[106:107], v[66:67], v[66:67] op_sel_hi:[0,1]
	v_sub_f32_e32 v66, v93, v68
	v_exp_f32_e32 v89, v66
	v_sub_f32_e32 v66, v109, v68
	v_exp_f32_e32 v91, v66
	v_sub_f32_e32 v66, v94, v68
	v_exp_f32_e32 v92, v66
	v_sub_f32_e32 v66, v110, v68
	v_exp_f32_e32 v106, v66
	v_sub_f32_e32 v66, v113, v68
	v_add_f32_e32 v93, v89, v91
	v_exp_f32_e32 v110, v66
	v_pk_add_f32 v[66:67], v[92:93], v[106:107]
	v_cvt_pk_bf16_f32 v171, v90, v89
	v_pk_add_f32 v[108:109], v[66:67], v[66:67] op_sel_hi:[0,1]
	v_sub_f32_e32 v66, v95, v68
	v_exp_f32_e32 v93, v66
	v_sub_f32_e32 v66, v111, v68
	v_exp_f32_e32 v107, v66
	v_sub_f32_e32 v66, v96, v68
	v_exp_f32_e32 v94, v66
	v_sub_f32_e32 v66, v112, v68
	v_exp_f32_e32 v108, v66
	v_add_f32_e32 v95, v93, v107
	v_exp_f32_e64 v96, -v68
	v_add_f32_e32 v212, v97, v110
	v_pk_add_f32 v[66:67], v[94:95], v[108:109]
	v_cvt_pk_bf16_f32 v172, v92, v93
	v_pk_add_f32 v[66:67], v[66:67], v[66:67] op_sel:[0,1] op_sel_hi:[1,0]
	v_pk_mul_f32 v[48:49], v[48:49], v[96:97] op_sel_hi:[1,0]
	v_mov_b32_e32 v67, v68
	v_pk_add_f32 v[212:213], v[212:213], v[66:67]
	v_pk_mul_f32 v[46:47], v[46:47], v[96:97] op_sel_hi:[1,0]
	v_xor_b32_e32 v66, 0x80000000, v213
	v_mov_b32_e32 v67, v66
	v_mov_b32_e32 v68, v66
	v_mov_b32_e32 v69, v66
	v_mov_b32_e32 v70, v66
	v_mov_b32_e32 v71, v66
	v_mov_b32_e32 v72, v66
	v_mov_b32_e32 v73, v66
	v_mov_b32_e32 v74, v66
	v_mov_b32_e32 v75, v66
	v_mov_b32_e32 v76, v66
	v_mov_b32_e32 v77, v66
	v_mov_b32_e32 v78, v66
	v_mov_b32_e32 v79, v66
	v_mov_b32_e32 v80, v66
	v_mov_b32_e32 v81, v66
	v_pk_mul_f32 v[44:45], v[44:45], v[96:97] op_sel_hi:[1,0]
	v_pk_mul_f32 v[42:43], v[42:43], v[96:97] op_sel_hi:[1,0]
	v_pk_mul_f32 v[40:41], v[40:41], v[96:97] op_sel_hi:[1,0]
	v_pk_mul_f32 v[38:39], v[38:39], v[96:97] op_sel_hi:[1,0]
	v_pk_mul_f32 v[36:37], v[36:37], v[96:97] op_sel_hi:[1,0]
	v_pk_mul_f32 v[34:35], v[34:35], v[96:97] op_sel_hi:[1,0]
	v_pk_mul_f32 v[64:65], v[64:65], v[96:97] op_sel_hi:[1,0]
	v_pk_mul_f32 v[62:63], v[62:63], v[96:97] op_sel_hi:[1,0]
	v_pk_mul_f32 v[60:61], v[60:61], v[96:97] op_sel_hi:[1,0]
	v_pk_mul_f32 v[58:59], v[58:59], v[96:97] op_sel_hi:[1,0]
	v_pk_mul_f32 v[56:57], v[56:57], v[96:97] op_sel_hi:[1,0]
	v_pk_mul_f32 v[54:55], v[54:55], v[96:97] op_sel_hi:[1,0]
	v_pk_mul_f32 v[52:53], v[52:53], v[96:97] op_sel_hi:[1,0]
	v_pk_mul_f32 v[50:51], v[50:51], v[96:97] op_sel_hi:[1,0]
	v_pk_mul_f32 v[32:33], v[32:33], v[96:97] op_sel_hi:[1,0]
	v_pk_mul_f32 v[30:31], v[30:31], v[96:97] op_sel_hi:[1,0]
	v_pk_mul_f32 v[28:29], v[28:29], v[96:97] op_sel_hi:[1,0]
	v_pk_mul_f32 v[26:27], v[26:27], v[96:97] op_sel_hi:[1,0]
	v_pk_mul_f32 v[24:25], v[24:25], v[96:97] op_sel_hi:[1,0]
	v_pk_mul_f32 v[22:23], v[22:23], v[96:97] op_sel_hi:[1,0]
	v_pk_mul_f32 v[20:21], v[20:21], v[96:97] op_sel_hi:[1,0]
	v_pk_mul_f32 v[18:19], v[18:19], v[96:97] op_sel_hi:[1,0]
	v_pk_mul_f32 v[16:17], v[16:17], v[96:97] op_sel_hi:[1,0]
	v_pk_mul_f32 v[14:15], v[14:15], v[96:97] op_sel_hi:[1,0]
	v_pk_mul_f32 v[12:13], v[12:13], v[96:97] op_sel_hi:[1,0]
	v_pk_mul_f32 v[10:11], v[10:11], v[96:97] op_sel_hi:[1,0]
	v_pk_mul_f32 v[8:9], v[8:9], v[96:97] op_sel_hi:[1,0]
	v_pk_mul_f32 v[6:7], v[6:7], v[96:97] op_sel_hi:[1,0]
	v_pk_mul_f32 v[4:5], v[4:5], v[96:97] op_sel_hi:[1,0]
	v_pk_mul_f32 v[2:3], v[2:3], v[96:97] op_sel_hi:[1,0]
	v_mul_f32_e32 v242, v242, v96
	v_cvt_pk_bf16_f32 v173, v94, v97
	v_cvt_pk_bf16_f32 v186, v86, v105
	v_cvt_pk_bf16_f32 v187, v88, v91
	v_cvt_pk_bf16_f32 v188, v106, v107
	v_cvt_pk_bf16_f32 v189, v108, v110

.LBB0_291:
	s_waitcnt lgkmcnt(3)
	v_mfma_f32_32x32x16_bf16 v[50:65], v[126:129], v[162:165], v[50:65]
	ds_read_b128 v[126:129], v0 offset:49152
	s_nop 1
	v_exp_f32_e32 v132, v82
	v_exp_f32_e32 v133, v83
	s_waitcnt lgkmcnt(3)
	v_mfma_f32_32x32x16_bf16 v[34:49], v[122:125], v[162:165], v[34:49]
	ds_read_b128 v[122:125], v0 offset:53248
	v_exp_f32_e32 v134, v84
	v_exp_f32_e32 v135, v85
	v_add_f32_e32 v136, v1, v132
	v_add_f32_e32 v137, v1, v133
	v_cvt_pk_bf16_f32 v166, v132, v133
	s_add_i32 s21, s22, 2
	s_cmp_lt_u32 s21, s18
	s_cselect_b64 s[26:27], -1, 0
	s_cmp_ge_u32 s21, s18
	s_cbranch_scc1 .LBB0_293
	s_lshl_b32 s37, s28, 14
	s_add_i32 m0, s10, s37
	s_add_u32 s100, s8, s80
	s_addc_u32 s101, s9, s81
	global_load_lds_dwordx4 v214, s[100:101]
.LBB0_293:
	s_waitcnt lgkmcnt(3)
	v_mfma_f32_32x32x16_bf16 v[18:33], v[118:121], v[162:165], v[18:33]
	ds_read_b128 v[118:121], v0 offset:57344
	v_exp_f32_e32 v132, v86
	v_exp_f32_e32 v133, v87
	v_add_f32_e32 v136, v136, v134
	v_add_f32_e32 v137, v137, v135
	v_cvt_pk_bf16_f32 v167, v134, v135
	s_waitcnt lgkmcnt(3)
	v_mfma_f32_32x32x16_bf16 v[2:17], v[114:117], v[162:165], v[2:17]
	ds_read_b128 v[114:117], v0 offset:61440
	v_exp_f32_e32 v134, v88
	v_exp_f32_e32 v135, v89
	v_add_f32_e32 v136, v136, v132
	v_add_f32_e32 v137, v137, v133
	v_cvt_pk_bf16_f32 v168, v132, v133
	s_waitcnt lgkmcnt(3)
	v_mfma_f32_32x32x16_bf16 v[50:65], v[126:129], v[170:173], v[50:65]
	v_add_u32_e32 v0, s36, v247
	ds_read_b128 v[126:129], v0 offset:49152
	v_exp_f32_e32 v132, v90
	v_exp_f32_e32 v133, v91
	v_add_f32_e32 v136, v136, v134
	v_add_f32_e32 v137, v137, v135
	v_cvt_pk_bf16_f32 v169, v134, v135
	s_waitcnt lgkmcnt(3)
	v_mfma_f32_32x32x16_bf16 v[34:49], v[122:125], v[170:173], v[34:49]
	ds_read_b128 v[122:125], v0 offset:53248
	v_exp_f32_e32 v134, v92
	v_exp_f32_e32 v135, v93
	v_add_f32_e32 v136, v136, v132
	v_add_f32_e32 v137, v137, v133
	v_cvt_pk_bf16_f32 v174, v132, v133
	s_andn2_b64 vcc, exec, s[26:27]
	s_cbranch_vccnz .LBB0_295
	s_lshl_b32 s26, s28, 14
	s_add_i32 s26, s10, s26
	s_add_i32 m0, s26, 0x2000
	s_add_u32 s100, s8, s62
	s_addc_u32 s101, s9, s63
	global_load_lds_dwordx4 v214, s[100:101]
.LBB0_295:
	s_waitcnt lgkmcnt(3)
	v_mfma_f32_32x32x16_bf16 v[18:33], v[118:121], v[170:173], v[18:33]
	ds_read_b128 v[118:121], v0 offset:57344
	v_exp_f32_e32 v132, v94
	v_exp_f32_e32 v133, v95
	v_add_f32_e32 v136, v136, v134
	v_add_f32_e32 v137, v137, v135
	v_cvt_pk_bf16_f32 v175, v134, v135
	s_waitcnt lgkmcnt(3)
	v_mfma_f32_32x32x16_bf16 v[2:17], v[114:117], v[170:173], v[2:17]
	ds_read_b128 v[114:117], v0 offset:61440
	v_exp_f32_e32 v134, v96
	v_exp_f32_e32 v135, v97
	v_add_f32_e32 v136, v136, v132
	v_add_f32_e32 v137, v137, v133
	v_cvt_pk_bf16_f32 v176, v132, v133
	s_waitcnt lgkmcnt(3)
	v_mfma_f32_32x32x16_bf16 v[50:65], v[126:129], v[178:181], v[50:65]
	v_add_u32_e32 v0, s36, v248
	ds_read_b128 v[126:129], v0 offset:49152
	v_exp_f32_e32 v132, v98
	v_exp_f32_e32 v133, v99
	v_add_f32_e32 v136, v136, v134
	v_add_f32_e32 v137, v137, v135
	v_cvt_pk_bf16_f32 v177, v134, v135
	s_waitcnt lgkmcnt(3)
	v_mfma_f32_32x32x16_bf16 v[34:49], v[122:125], v[178:181], v[34:49]
	v_exp_f32_e32 v134, v100
	v_exp_f32_e32 v135, v101
	v_add_f32_e32 v136, v136, v132
	v_add_f32_e32 v137, v137, v133
	v_cvt_pk_bf16_f32 v182, v132, v133
	ds_read_b128 v[122:125], v0 offset:53248
	v_cndmask_b32_e64 v138, 0, 1, s[44:45]
	v_cmp_ne_u32_e64 s[40:41], 1, v138
	s_andn2_b64 vcc, exec, s[44:45]
	s_cbranch_vccnz .LBB0_297
	s_lshl_b32 s26, s23, 14
	s_add_i32 s26, s10, s26
	s_add_i32 m0, s26, 0xc000
	s_add_u32 s100, s8, s96
	s_addc_u32 s101, s9, s97
	global_load_lds_dwordx4 v216, s[100:101]
.LBB0_297:
	s_waitcnt lgkmcnt(3)
	v_mfma_f32_32x32x16_bf16 v[18:33], v[118:121], v[178:181], v[18:33]
	ds_read_b128 v[118:121], v0 offset:57344
	v_exp_f32_e32 v132, v102
	v_exp_f32_e32 v133, v103
	v_add_f32_e32 v136, v136, v134
	v_add_f32_e32 v137, v137, v135
	v_cvt_pk_bf16_f32 v183, v134, v135
	s_waitcnt lgkmcnt(3)
	v_mfma_f32_32x32x16_bf16 v[2:17], v[114:117], v[178:181], v[2:17]
	ds_read_b128 v[114:117], v0 offset:61440
	v_exp_f32_e32 v134, v104
	v_exp_f32_e32 v135, v105
	v_add_f32_e32 v136, v136, v132
	v_add_f32_e32 v137, v137, v133
	v_cvt_pk_bf16_f32 v184, v132, v133
	s_waitcnt lgkmcnt(3)
	v_mfma_f32_32x32x16_bf16 v[50:65], v[126:129], v[186:189], v[50:65]
	v_exp_f32_e32 v132, v106
	v_exp_f32_e32 v133, v107
	v_add_f32_e32 v136, v136, v134
	v_add_f32_e32 v137, v137, v135
	v_cvt_pk_bf16_f32 v185, v134, v135
	s_waitcnt lgkmcnt(2)
	v_mfma_f32_32x32x16_bf16 v[34:49], v[122:125], v[186:189], v[34:49]
	v_exp_f32_e32 v134, v108
	v_exp_f32_e32 v135, v109
	v_add_f32_e32 v136, v136, v132
	v_add_f32_e32 v137, v137, v133
	v_cvt_pk_bf16_f32 v190, v132, v133
	s_and_b64 vcc, exec, s[40:41]
	s_cbranch_vccnz .LBB0_299
	s_lshl_b32 s26, s23, 14
	s_add_i32 s26, s10, s26
	s_add_i32 m0, s26, 0xe000
	s_add_u32 s100, s8, s58
	s_addc_u32 s101, s9, s59
	global_load_lds_dwordx4 v216, s[100:101]
.LBB0_299:
	s_waitcnt lgkmcnt(1)
	v_mfma_f32_32x32x16_bf16 v[18:33], v[118:121], v[186:189], v[18:33]
	v_exp_f32_e32 v132, v110
	v_exp_f32_e32 v133, v111
	v_add_f32_e32 v136, v136, v134
	v_add_f32_e32 v137, v137, v135
	v_cvt_pk_bf16_f32 v191, v134, v135
	s_waitcnt lgkmcnt(0)
	v_mfma_f32_32x32x16_bf16 v[2:17], v[114:117], v[186:189], v[2:17]
	v_exp_f32_e32 v134, v112
	v_exp_f32_e32 v135, v113
	v_add_f32_e32 v136, v136, v132
	v_add_f32_e32 v137, v137, v133
	v_cvt_pk_bf16_f32 v192, v132, v133
	v_add_f32_e32 v136, v136, v134
	v_add_f32_e32 v137, v137, v135
	v_cvt_pk_bf16_f32 v193, v134, v135
	v_add_f32_e32 v212, v136, v137
	v_cmp_nge_f32_e32 vcc, s7, v212
	s_cbranch_vccz .LBB0_301
	v_max_f32_e32 v0, v99, v99
	v_max_f32_e32 v66, v83, v83
	v_max_f32_e32 v0, v66, v0
	v_max3_f32 v0, v82, v98, v0
	v_max3_f32 v66, v100, v85, v101
	v_max3_f32 v0, v0, v84, v66
	v_max3_f32 v66, v102, v87, v103
	v_max3_f32 v0, v0, v86, v66
	v_max3_f32 v66, v104, v89, v105
	v_max3_f32 v0, v0, v88, v66
	v_max3_f32 v66, v106, v91, v107
	v_max3_f32 v0, v0, v90, v66
	v_max3_f32 v66, v108, v93, v109
	v_max3_f32 v0, v0, v92, v66
	v_max3_f32 v66, v110, v95, v111
	v_max3_f32 v0, v0, v94, v66
	v_max3_f32 v66, v112, v97, v113
	v_max3_f32 v0, v0, v96, v66
	v_mov_b32_e32 v66, v0
	s_nop 1
	v_permlane32_swap_b32_e32 v0, v66
	v_max_f32_e32 v66, v66, v66
	v_max_f32_e32 v0, v0, v0
	v_max_f32_e32 v0, v0, v66
	v_cmp_lt_f32_e32 vcc, s57, v0
	s_nop 1
	v_cndmask_b32_e32 v68, 0, v0, vcc
	v_sub_f32_e32 v0, v82, v68
	v_exp_f32_e32 v116, v0
	v_sub_f32_e32 v0, v98, v68
	v_exp_f32_e32 v117, v0
	v_sub_f32_e32 v0, v83, v68
	v_exp_f32_e32 v118, v0
	v_sub_f32_e32 v0, v99, v68
	v_exp_f32_e32 v119, v0
	v_sub_f32_e32 v0, v84, v68
	v_exp_f32_e32 v98, v0
	v_sub_f32_e32 v0, v100, v68
	v_exp_f32_e32 v82, v0
	v_add_f32_e32 v0, v117, v116
	v_add_f32_e32 v99, 0, v0
	v_add_f32_e32 v83, v119, v118
	v_sub_f32_e32 v0, v85, v68
	v_pk_add_f32 v[66:67], v[82:83], v[98:99]
	v_exp_f32_e32 v83, v0
	v_sub_f32_e32 v0, v101, v68
	v_pk_add_f32 v[114:115], v[66:67], v[66:67] op_sel_hi:[0,1]
	v_exp_f32_e32 v99, v0
	v_sub_f32_e32 v0, v86, v68
	v_exp_f32_e32 v114, v0
	v_sub_f32_e32 v0, v102, v68
	v_exp_f32_e32 v84, v0
	v_add_f32_e32 v85, v99, v83
	v_sub_f32_e32 v0, v87, v68
	v_cvt_pk_bf16_f32 v166, v116, v118
	v_pk_add_f32 v[66:67], v[84:85], v[114:115]
	v_exp_f32_e32 v85, v0
	v_sub_f32_e32 v0, v103, v68
	v_pk_add_f32 v[100:101], v[66:67], v[66:67] op_sel_hi:[0,1]
	v_exp_f32_e32 v115, v0
	v_sub_f32_e32 v0, v88, v68
	v_exp_f32_e32 v100, v0
	v_sub_f32_e32 v0, v104, v68
	v_exp_f32_e32 v86, v0
	v_add_f32_e32 v87, v115, v85
	v_sub_f32_e32 v0, v89, v68
	v_cvt_pk_bf16_f32 v167, v98, v83
	v_pk_add_f32 v[66:67], v[86:87], v[100:101]
	v_exp_f32_e32 v87, v0
	v_sub_f32_e32 v0, v105, v68
	v_pk_add_f32 v[102:103], v[66:67], v[66:67] op_sel_hi:[0,1]
	v_exp_f32_e32 v101, v0
	v_sub_f32_e32 v0, v90, v68
	v_exp_f32_e32 v102, v0
	v_sub_f32_e32 v0, v106, v68
	v_exp_f32_e32 v88, v0
	v_add_f32_e32 v89, v101, v87
	v_sub_f32_e32 v0, v91, v68
	v_cvt_pk_bf16_f32 v168, v114, v85
	v_pk_add_f32 v[66:67], v[88:89], v[102:103]
	v_exp_f32_e32 v89, v0
	v_sub_f32_e32 v0, v107, v68
	v_pk_add_f32 v[104:105], v[66:67], v[66:67] op_sel_hi:[0,1]
	v_exp_f32_e32 v103, v0
	v_sub_f32_e32 v0, v92, v68
	v_exp_f32_e32 v104, v0
	v_sub_f32_e32 v0, v108, v68
	v_exp_f32_e32 v90, v0
	v_sub_f32_e32 v0, v97, v68
	v_exp_f32_e32 v97, v0
	v_add_f32_e32 v91, v103, v89
	v_sub_f32_e32 v0, v93, v68
	v_pk_add_f32 v[66:67], v[90:91], v[104:105]
	v_exp_f32_e32 v91, v0
	v_sub_f32_e32 v0, v109, v68
	v_pk_add_f32 v[106:107], v[66:67], v[66:67] op_sel_hi:[0,1]
	v_exp_f32_e32 v105, v0
	v_sub_f32_e32 v0, v94, v68
	v_exp_f32_e32 v106, v0
	v_sub_f32_e32 v0, v110, v68
	v_exp_f32_e32 v92, v0
	v_sub_f32_e32 v0, v113, v68
	v_exp_f32_e32 v110, v0
	v_add_f32_e32 v93, v105, v91
	v_sub_f32_e32 v0, v95, v68
	v_pk_add_f32 v[66:67], v[92:93], v[106:107]
	v_exp_f32_e32 v93, v0
	v_sub_f32_e32 v0, v111, v68
	v_pk_add_f32 v[108:109], v[66:67], v[66:67] op_sel_hi:[0,1]
	v_exp_f32_e32 v107, v0
	v_sub_f32_e32 v0, v96, v68
	v_exp_f32_e32 v108, v0
	v_sub_f32_e32 v0, v112, v68
	v_exp_f32_e32 v94, v0
	v_add_f32_e32 v95, v107, v93
	v_exp_f32_e64 v0, -v68
	v_add_f32_e32 v212, v110, v97
	v_pk_add_f32 v[66:67], v[94:95], v[108:109]
	v_cvt_pk_bf16_f32 v169, v100, v87
	v_pk_add_f32 v[66:67], v[66:67], v[66:67] op_sel:[0,1] op_sel_hi:[1,0]
	v_pk_mul_f32 v[64:65], v[64:65], v[0:1] op_sel_hi:[1,0]
	v_mov_b32_e32 v67, v68
	v_pk_add_f32 v[212:213], v[212:213], v[66:67]
	v_pk_mul_f32 v[62:63], v[62:63], v[0:1] op_sel_hi:[1,0]
	v_xor_b32_e32 v66, 0x80000000, v213
	v_mov_b32_e32 v67, v66
	v_mov_b32_e32 v68, v66
	v_mov_b32_e32 v69, v66
	v_mov_b32_e32 v70, v66
	v_mov_b32_e32 v71, v66
	v_mov_b32_e32 v72, v66
	v_mov_b32_e32 v73, v66
	v_mov_b32_e32 v74, v66
	v_mov_b32_e32 v75, v66
	v_mov_b32_e32 v76, v66
	v_mov_b32_e32 v77, v66
	v_mov_b32_e32 v78, v66
	v_mov_b32_e32 v79, v66
	v_mov_b32_e32 v80, v66
	v_mov_b32_e32 v81, v66
	v_pk_mul_f32 v[60:61], v[60:61], v[0:1] op_sel_hi:[1,0]
	v_pk_mul_f32 v[58:59], v[58:59], v[0:1] op_sel_hi:[1,0]
	v_pk_mul_f32 v[56:57], v[56:57], v[0:1] op_sel_hi:[1,0]
	v_pk_mul_f32 v[54:55], v[54:55], v[0:1] op_sel_hi:[1,0]
	v_pk_mul_f32 v[52:53], v[52:53], v[0:1] op_sel_hi:[1,0]
	v_pk_mul_f32 v[50:51], v[50:51], v[0:1] op_sel_hi:[1,0]
	v_pk_mul_f32 v[48:49], v[48:49], v[0:1] op_sel_hi:[1,0]
	v_pk_mul_f32 v[46:47], v[46:47], v[0:1] op_sel_hi:[1,0]
	v_pk_mul_f32 v[44:45], v[44:45], v[0:1] op_sel_hi:[1,0]
	v_pk_mul_f32 v[42:43], v[42:43], v[0:1] op_sel_hi:[1,0]
	v_pk_mul_f32 v[40:41], v[40:41], v[0:1] op_sel_hi:[1,0]
	v_pk_mul_f32 v[38:39], v[38:39], v[0:1] op_sel_hi:[1,0]
	v_pk_mul_f32 v[36:37], v[36:37], v[0:1] op_sel_hi:[1,0]
	v_pk_mul_f32 v[34:35], v[34:35], v[0:1] op_sel_hi:[1,0]
	v_pk_mul_f32 v[32:33], v[32:33], v[0:1] op_sel_hi:[1,0]
	v_pk_mul_f32 v[30:31], v[30:31], v[0:1] op_sel_hi:[1,0]
	v_pk_mul_f32 v[28:29], v[28:29], v[0:1] op_sel_hi:[1,0]
	v_pk_mul_f32 v[26:27], v[26:27], v[0:1] op_sel_hi:[1,0]
	v_pk_mul_f32 v[24:25], v[24:25], v[0:1] op_sel_hi:[1,0]
	v_pk_mul_f32 v[22:23], v[22:23], v[0:1] op_sel_hi:[1,0]
	v_pk_mul_f32 v[20:21], v[20:21], v[0:1] op_sel_hi:[1,0]
	v_pk_mul_f32 v[18:19], v[18:19], v[0:1] op_sel_hi:[1,0]
	v_pk_mul_f32 v[16:17], v[16:17], v[0:1] op_sel_hi:[1,0]
	v_pk_mul_f32 v[14:15], v[14:15], v[0:1] op_sel_hi:[1,0]
	v_pk_mul_f32 v[12:13], v[12:13], v[0:1] op_sel_hi:[1,0]
	v_pk_mul_f32 v[10:11], v[10:11], v[0:1] op_sel_hi:[1,0]
	v_pk_mul_f32 v[8:9], v[8:9], v[0:1] op_sel_hi:[1,0]
	v_pk_mul_f32 v[6:7], v[6:7], v[0:1] op_sel_hi:[1,0]
	v_pk_mul_f32 v[4:5], v[4:5], v[0:1] op_sel_hi:[1,0]
	v_pk_mul_f32 v[2:3], v[2:3], v[0:1] op_sel_hi:[1,0]
	v_mul_f32_e32 v243, v243, v0
	v_cvt_pk_bf16_f32 v174, v102, v89
	v_cvt_pk_bf16_f32 v175, v104, v91
	v_cvt_pk_bf16_f32 v176, v106, v93
	v_cvt_pk_bf16_f32 v177, v108, v97
	v_cvt_pk_bf16_f32 v182, v117, v119
	v_cvt_pk_bf16_f32 v183, v82, v99
	v_cvt_pk_bf16_f32 v184, v84, v115
	v_cvt_pk_bf16_f32 v185, v86, v101
	v_cvt_pk_bf16_f32 v190, v88, v103
	v_cvt_pk_bf16_f32 v191, v90, v105
	v_cvt_pk_bf16_f32 v192, v92, v107
	v_cvt_pk_bf16_f32 v193, v94, v110

.LBB0_331:
	s_waitcnt lgkmcnt(3)
	v_mfma_f32_32x32x16_bf16 v[50:65], v[126:129], v[166:169], v[50:65]
	ds_read_b128 v[126:129], v0 offset:49152
	s_nop 0
	v_exp_f32_e32 v132, v82
	v_exp_f32_e32 v133, v83
	s_waitcnt lgkmcnt(3)
	v_mfma_f32_32x32x16_bf16 v[34:49], v[122:125], v[166:169], v[34:49]
	ds_read_b128 v[122:125], v0 offset:53248
	v_exp_f32_e32 v134, v84
	v_exp_f32_e32 v135, v85
	v_add_f32_e32 v136, v1, v132
	v_add_f32_e32 v137, v1, v133
	v_cvt_pk_bf16_f32 v162, v132, v133
	s_add_i32 s22, s22, 3
	s_cmp_le_u32 s22, s17
	s_cselect_b64 s[26:27], -1, 0
	s_cmp_gt_u32 s22, s17
	s_cbranch_scc1 .LBB0_333
	s_lshl_b32 s22, s28, 14
	s_add_u32 s100, s8, s50
	s_addc_u32 s101, s9, s51
	s_add_i32 m0, s10, s22
	s_nop 0
	global_load_lds_dwordx4 v214, s[100:101]
.LBB0_333:
	s_waitcnt lgkmcnt(3)
	v_mfma_f32_32x32x16_bf16 v[18:33], v[118:121], v[166:169], v[18:33]
	ds_read_b128 v[118:121], v0 offset:57344
	v_exp_f32_e32 v132, v86
	v_exp_f32_e32 v133, v87
	v_add_f32_e32 v136, v136, v134
	v_add_f32_e32 v137, v137, v135
	v_cvt_pk_bf16_f32 v163, v134, v135
	s_waitcnt lgkmcnt(3)
	v_mfma_f32_32x32x16_bf16 v[2:17], v[114:117], v[166:169], v[2:17]
	ds_read_b128 v[114:117], v0 offset:61440
	v_exp_f32_e32 v134, v88
	v_exp_f32_e32 v135, v89
	v_add_f32_e32 v136, v136, v132
	v_add_f32_e32 v137, v137, v133
	v_cvt_pk_bf16_f32 v164, v132, v133
	s_waitcnt lgkmcnt(3)
	v_mfma_f32_32x32x16_bf16 v[50:65], v[126:129], v[174:177], v[50:65]
	v_add_u32_e32 v0, s36, v247
	ds_read_b128 v[126:129], v0 offset:49152
	v_exp_f32_e32 v132, v90
	v_exp_f32_e32 v133, v91
	v_add_f32_e32 v136, v136, v134
	v_add_f32_e32 v137, v137, v135
	v_cvt_pk_bf16_f32 v165, v134, v135
	s_waitcnt lgkmcnt(3)
	v_mfma_f32_32x32x16_bf16 v[34:49], v[122:125], v[174:177], v[34:49]
	ds_read_b128 v[122:125], v0 offset:53248
	v_exp_f32_e32 v134, v92
	v_exp_f32_e32 v135, v93
	v_add_f32_e32 v136, v136, v132
	v_add_f32_e32 v137, v137, v133
	v_cvt_pk_bf16_f32 v170, v132, v133
	s_andn2_b64 vcc, exec, s[26:27]
	s_cbranch_vccnz .LBB0_335
	s_lshl_b32 s22, s28, 14
	s_add_i32 s22, s10, s22
	s_add_u32 s100, s8, s4
	s_addc_u32 s101, s9, s5
	s_add_i32 m0, s22, 0x2000
	s_nop 0
	global_load_lds_dwordx4 v214, s[100:101]
.LBB0_335:
	s_waitcnt lgkmcnt(3)
	v_mfma_f32_32x32x16_bf16 v[18:33], v[118:121], v[174:177], v[18:33]
	ds_read_b128 v[118:121], v0 offset:57344
	v_exp_f32_e32 v132, v94
	v_exp_f32_e32 v133, v95
	v_add_f32_e32 v136, v136, v134
	v_add_f32_e32 v137, v137, v135
	v_cvt_pk_bf16_f32 v171, v134, v135
	s_waitcnt lgkmcnt(3)
	v_mfma_f32_32x32x16_bf16 v[2:17], v[114:117], v[174:177], v[2:17]
	ds_read_b128 v[114:117], v0 offset:61440
	v_exp_f32_e32 v134, v96
	v_exp_f32_e32 v135, v97
	v_add_f32_e32 v136, v136, v132
	v_add_f32_e32 v137, v137, v133
	v_cvt_pk_bf16_f32 v172, v132, v133
	s_waitcnt lgkmcnt(3)
	v_mfma_f32_32x32x16_bf16 v[50:65], v[126:129], v[182:185], v[50:65]
	v_add_u32_e32 v0, s36, v248
	ds_read_b128 v[126:129], v0 offset:49152
	v_exp_f32_e32 v132, v98
	v_exp_f32_e32 v133, v99
	v_add_f32_e32 v136, v136, v134
	v_add_f32_e32 v137, v137, v135
	v_cvt_pk_bf16_f32 v173, v134, v135
	s_waitcnt lgkmcnt(3)
	v_mfma_f32_32x32x16_bf16 v[34:49], v[122:125], v[182:185], v[34:49]
	v_exp_f32_e32 v134, v100
	v_exp_f32_e32 v135, v101
	v_add_f32_e32 v136, v136, v132
	v_add_f32_e32 v137, v137, v133
	v_cvt_pk_bf16_f32 v178, v132, v133
	ds_read_b128 v[122:125], v0 offset:53248
	v_cndmask_b32_e64 v138, 0, 1, s[44:45]
	v_cmp_ne_u32_e64 s[40:41], 1, v138
	s_andn2_b64 vcc, exec, s[44:45]
	s_cbranch_vccnz .LBB0_337
	s_lshl_b32 s22, s23, 14
	s_add_i32 s22, s10, s22
	s_add_i32 m0, s22, 0xc000
	s_add_u32 s100, s8, s0
	s_addc_u32 s101, s9, s1
	global_load_lds_dwordx4 v216, s[100:101]
.LBB0_337:
	s_waitcnt lgkmcnt(3)
	v_mfma_f32_32x32x16_bf16 v[18:33], v[118:121], v[182:185], v[18:33]
	ds_read_b128 v[118:121], v0 offset:57344
	v_exp_f32_e32 v132, v102
	v_exp_f32_e32 v133, v103
	v_add_f32_e32 v136, v136, v134
	v_add_f32_e32 v137, v137, v135
	v_cvt_pk_bf16_f32 v179, v134, v135
	s_waitcnt lgkmcnt(3)
	v_mfma_f32_32x32x16_bf16 v[2:17], v[114:117], v[182:185], v[2:17]
	ds_read_b128 v[114:117], v0 offset:61440
	v_exp_f32_e32 v134, v104
	v_exp_f32_e32 v135, v105
	v_add_f32_e32 v136, v136, v132
	v_add_f32_e32 v137, v137, v133
	v_cvt_pk_bf16_f32 v180, v132, v133
	s_waitcnt lgkmcnt(3)
	v_mfma_f32_32x32x16_bf16 v[50:65], v[126:129], v[190:193], v[50:65]
	v_exp_f32_e32 v132, v106
	v_exp_f32_e32 v133, v107
	v_add_f32_e32 v136, v136, v134
	v_add_f32_e32 v137, v137, v135
	v_cvt_pk_bf16_f32 v181, v134, v135
	s_waitcnt lgkmcnt(2)
	v_mfma_f32_32x32x16_bf16 v[34:49], v[122:125], v[190:193], v[34:49]
	v_exp_f32_e32 v134, v108
	v_exp_f32_e32 v135, v109
	v_add_f32_e32 v136, v136, v132
	v_add_f32_e32 v137, v137, v133
	v_cvt_pk_bf16_f32 v186, v132, v133
	s_and_b64 vcc, exec, s[40:41]
	s_cbranch_vccnz .LBB0_339
	s_lshl_b32 s22, s23, 14
	s_add_i32 s22, s10, s22
	s_add_u32 s100, s8, s52
	s_addc_u32 s101, s9, s53
	s_add_i32 m0, s22, 0xe000
	s_nop 0
	global_load_lds_dwordx4 v216, s[100:101]
.LBB0_339:
	s_waitcnt lgkmcnt(1)
	v_mfma_f32_32x32x16_bf16 v[18:33], v[118:121], v[190:193], v[18:33]
	v_exp_f32_e32 v132, v110
	v_exp_f32_e32 v133, v111
	v_add_f32_e32 v136, v136, v134
	v_add_f32_e32 v137, v137, v135
	v_cvt_pk_bf16_f32 v187, v134, v135
	s_waitcnt lgkmcnt(0)
	v_mfma_f32_32x32x16_bf16 v[2:17], v[114:117], v[190:193], v[2:17]
	v_exp_f32_e32 v134, v112
	v_exp_f32_e32 v135, v113
	v_add_f32_e32 v136, v136, v132
	v_add_f32_e32 v137, v137, v133
	v_cvt_pk_bf16_f32 v188, v132, v133
	v_add_f32_e32 v136, v136, v134
	v_add_f32_e32 v137, v137, v135
	v_cvt_pk_bf16_f32 v189, v134, v135
	v_add_f32_e32 v212, v136, v137
	v_cmp_nge_f32_e32 vcc, s7, v212
	s_cbranch_vccz .LBB0_341
	v_max_f32_e32 v0, v99, v99
	v_max_f32_e32 v66, v83, v83
	v_max_f32_e32 v0, v66, v0
	v_max3_f32 v0, v82, v98, v0
	v_max3_f32 v66, v100, v85, v101
	v_max3_f32 v0, v0, v84, v66
	v_max3_f32 v66, v102, v87, v103
	v_max3_f32 v0, v0, v86, v66
	v_max3_f32 v66, v104, v89, v105
	v_max3_f32 v0, v0, v88, v66
	v_max3_f32 v66, v106, v91, v107
	v_max3_f32 v0, v0, v90, v66
	v_max3_f32 v66, v108, v93, v109
	v_max3_f32 v0, v0, v92, v66
	v_max3_f32 v66, v110, v95, v111
	v_max3_f32 v0, v0, v94, v66
	v_max3_f32 v66, v112, v97, v113
	v_max3_f32 v0, v0, v96, v66
	v_mov_b32_e32 v66, v0
	s_nop 1
	v_permlane32_swap_b32_e32 v0, v66
	v_max_f32_e32 v66, v66, v66
	v_max_f32_e32 v0, v0, v0
	v_max_f32_e32 v0, v0, v66
	v_cmp_lt_f32_e32 vcc, s57, v0
	s_nop 1
	v_cndmask_b32_e32 v68, 0, v0, vcc
	v_sub_f32_e32 v0, v82, v68
	v_exp_f32_e32 v116, v0
	v_sub_f32_e32 v0, v98, v68
	v_exp_f32_e32 v117, v0
	v_sub_f32_e32 v0, v83, v68
	v_exp_f32_e32 v118, v0
	v_sub_f32_e32 v0, v99, v68
	v_exp_f32_e32 v119, v0
	v_sub_f32_e32 v0, v84, v68
	v_exp_f32_e32 v114, v0
	v_sub_f32_e32 v0, v100, v68
	v_exp_f32_e32 v82, v0
	v_add_f32_e32 v0, v116, v117
	v_add_f32_e32 v83, 0, v0
	v_add_f32_e32 v115, v118, v119
	v_sub_f32_e32 v0, v85, v68
	v_pk_add_f32 v[66:67], v[114:115], v[82:83]
	v_exp_f32_e32 v83, v0
	v_sub_f32_e32 v0, v101, v68
	v_exp_f32_e32 v115, v0
	v_sub_f32_e32 v0, v86, v68
	v_pk_add_f32 v[98:99], v[66:67], v[66:67] op_sel_hi:[0,1]
	v_exp_f32_e32 v100, v0
	v_sub_f32_e32 v0, v102, v68
	v_exp_f32_e32 v98, v0
	v_add_f32_e32 v101, v83, v115
	v_sub_f32_e32 v0, v87, v68
	v_cvt_pk_bf16_f32 v162, v116, v118
	v_pk_add_f32 v[66:67], v[100:101], v[98:99]
	v_exp_f32_e32 v99, v0
	v_sub_f32_e32 v0, v103, v68
	v_exp_f32_e32 v101, v0
	v_sub_f32_e32 v0, v88, v68
	v_pk_add_f32 v[84:85], v[66:67], v[66:67] op_sel_hi:[0,1]
	v_exp_f32_e32 v102, v0
	v_sub_f32_e32 v0, v104, v68
	v_exp_f32_e32 v84, v0
	v_add_f32_e32 v103, v99, v101
	v_sub_f32_e32 v0, v89, v68
	v_cvt_pk_bf16_f32 v163, v114, v83
	v_pk_add_f32 v[66:67], v[102:103], v[84:85]
	v_exp_f32_e32 v85, v0
	v_sub_f32_e32 v0, v105, v68
	v_exp_f32_e32 v103, v0
	v_sub_f32_e32 v0, v90, v68
	v_pk_add_f32 v[86:87], v[66:67], v[66:67] op_sel_hi:[0,1]
	v_exp_f32_e32 v104, v0
	v_sub_f32_e32 v0, v106, v68
	v_exp_f32_e32 v86, v0
	v_add_f32_e32 v105, v85, v103
	v_sub_f32_e32 v0, v91, v68
	v_cvt_pk_bf16_f32 v164, v100, v99
	v_pk_add_f32 v[66:67], v[104:105], v[86:87]
	v_exp_f32_e32 v87, v0
	v_sub_f32_e32 v0, v107, v68
	v_exp_f32_e32 v105, v0
	v_sub_f32_e32 v0, v92, v68
	v_pk_add_f32 v[88:89], v[66:67], v[66:67] op_sel_hi:[0,1]
	v_exp_f32_e32 v90, v0
	v_sub_f32_e32 v0, v108, v68
	v_exp_f32_e32 v88, v0
	v_sub_f32_e32 v0, v97, v68
	v_exp_f32_e32 v97, v0
	v_add_f32_e32 v91, v87, v105
	v_sub_f32_e32 v0, v93, v68
	v_pk_add_f32 v[66:67], v[90:91], v[88:89]
	v_exp_f32_e32 v89, v0
	v_sub_f32_e32 v0, v109, v68
	v_exp_f32_e32 v91, v0
	v_sub_f32_e32 v0, v94, v68
	v_pk_add_f32 v[106:107], v[66:67], v[66:67] op_sel_hi:[0,1]
	v_exp_f32_e32 v92, v0
	v_sub_f32_e32 v0, v110, v68
	v_exp_f32_e32 v106, v0
	v_sub_f32_e32 v0, v113, v68
	v_exp_f32_e32 v110, v0
	v_add_f32_e32 v93, v89, v91
	v_sub_f32_e32 v0, v95, v68
	v_pk_add_f32 v[66:67], v[92:93], v[106:107]
	v_exp_f32_e32 v93, v0
	v_sub_f32_e32 v0, v111, v68
	v_exp_f32_e32 v107, v0
	v_sub_f32_e32 v0, v96, v68
	v_pk_add_f32 v[108:109], v[66:67], v[66:67] op_sel_hi:[0,1]
	v_exp_f32_e32 v94, v0
	v_sub_f32_e32 v0, v112, v68
	v_exp_f32_e32 v108, v0
	v_add_f32_e32 v95, v93, v107
	v_exp_f32_e64 v0, -v68
	v_add_f32_e32 v212, v97, v110
	v_pk_add_f32 v[66:67], v[94:95], v[108:109]
	v_cvt_pk_bf16_f32 v165, v102, v85
	v_pk_add_f32 v[66:67], v[66:67], v[66:67] op_sel:[0,1] op_sel_hi:[1,0]
	v_pk_mul_f32 v[64:65], v[64:65], v[0:1] op_sel_hi:[1,0]
	v_mov_b32_e32 v67, v68
	v_pk_add_f32 v[212:213], v[212:213], v[66:67]
	v_pk_mul_f32 v[62:63], v[62:63], v[0:1] op_sel_hi:[1,0]
	v_xor_b32_e32 v66, 0x80000000, v213
	v_mov_b32_e32 v67, v66
	v_mov_b32_e32 v68, v66
	v_mov_b32_e32 v69, v66
	v_mov_b32_e32 v70, v66
	v_mov_b32_e32 v71, v66
	v_mov_b32_e32 v72, v66
	v_mov_b32_e32 v73, v66
	v_mov_b32_e32 v74, v66
	v_mov_b32_e32 v75, v66
	v_mov_b32_e32 v76, v66
	v_mov_b32_e32 v77, v66
	v_mov_b32_e32 v78, v66
	v_mov_b32_e32 v79, v66
	v_mov_b32_e32 v80, v66
	v_mov_b32_e32 v81, v66
	v_pk_mul_f32 v[60:61], v[60:61], v[0:1] op_sel_hi:[1,0]
	v_pk_mul_f32 v[58:59], v[58:59], v[0:1] op_sel_hi:[1,0]
	v_pk_mul_f32 v[56:57], v[56:57], v[0:1] op_sel_hi:[1,0]
	v_pk_mul_f32 v[54:55], v[54:55], v[0:1] op_sel_hi:[1,0]
	v_pk_mul_f32 v[52:53], v[52:53], v[0:1] op_sel_hi:[1,0]
	v_pk_mul_f32 v[50:51], v[50:51], v[0:1] op_sel_hi:[1,0]
	v_pk_mul_f32 v[48:49], v[48:49], v[0:1] op_sel_hi:[1,0]
	v_pk_mul_f32 v[46:47], v[46:47], v[0:1] op_sel_hi:[1,0]
	v_pk_mul_f32 v[44:45], v[44:45], v[0:1] op_sel_hi:[1,0]
	v_pk_mul_f32 v[42:43], v[42:43], v[0:1] op_sel_hi:[1,0]
	v_pk_mul_f32 v[40:41], v[40:41], v[0:1] op_sel_hi:[1,0]
	v_pk_mul_f32 v[38:39], v[38:39], v[0:1] op_sel_hi:[1,0]
	v_pk_mul_f32 v[36:37], v[36:37], v[0:1] op_sel_hi:[1,0]
	v_pk_mul_f32 v[34:35], v[34:35], v[0:1] op_sel_hi:[1,0]
	v_pk_mul_f32 v[32:33], v[32:33], v[0:1] op_sel_hi:[1,0]
	v_pk_mul_f32 v[30:31], v[30:31], v[0:1] op_sel_hi:[1,0]
	v_pk_mul_f32 v[28:29], v[28:29], v[0:1] op_sel_hi:[1,0]
	v_pk_mul_f32 v[26:27], v[26:27], v[0:1] op_sel_hi:[1,0]
	v_pk_mul_f32 v[24:25], v[24:25], v[0:1] op_sel_hi:[1,0]
	v_pk_mul_f32 v[22:23], v[22:23], v[0:1] op_sel_hi:[1,0]
	v_pk_mul_f32 v[20:21], v[20:21], v[0:1] op_sel_hi:[1,0]
	v_pk_mul_f32 v[18:19], v[18:19], v[0:1] op_sel_hi:[1,0]
	v_pk_mul_f32 v[16:17], v[16:17], v[0:1] op_sel_hi:[1,0]
	v_pk_mul_f32 v[14:15], v[14:15], v[0:1] op_sel_hi:[1,0]
	v_pk_mul_f32 v[12:13], v[12:13], v[0:1] op_sel_hi:[1,0]
	v_pk_mul_f32 v[10:11], v[10:11], v[0:1] op_sel_hi:[1,0]
	v_pk_mul_f32 v[8:9], v[8:9], v[0:1] op_sel_hi:[1,0]
	v_pk_mul_f32 v[6:7], v[6:7], v[0:1] op_sel_hi:[1,0]
	v_pk_mul_f32 v[4:5], v[4:5], v[0:1] op_sel_hi:[1,0]
	v_pk_mul_f32 v[2:3], v[2:3], v[0:1] op_sel_hi:[1,0]
	v_mul_f32_e32 v243, v243, v0
	v_cvt_pk_bf16_f32 v170, v104, v87
	v_cvt_pk_bf16_f32 v171, v90, v89
	v_cvt_pk_bf16_f32 v172, v92, v93
	v_cvt_pk_bf16_f32 v173, v94, v97
	v_cvt_pk_bf16_f32 v178, v117, v119
	v_cvt_pk_bf16_f32 v179, v82, v115
	v_cvt_pk_bf16_f32 v180, v98, v101
	v_cvt_pk_bf16_f32 v181, v84, v103
	v_cvt_pk_bf16_f32 v186, v86, v105
	v_cvt_pk_bf16_f32 v187, v88, v91
	v_cvt_pk_bf16_f32 v188, v106, v107
	v_cvt_pk_bf16_f32 v189, v108, v110
